# v082 bundle + NA: DMA address math skipped with skipped DMA, mask complements on SALU
# baseline (speedup 1.0000x reference)
.Lna_wj:
	s_barrier
	s_cmp_lg_u32 s100, 0
	s_cbranch_scc1 .Lna_nodma
	v_lshlrev_b64 v[66:67], 11, v[66:67]
	v_ashrrev_i32_e32 v69, 31, v68
	s_add_i32 s11, s11, 0
	v_lshl_add_u64 v[66:67], v[150:151], 0, v[66:67]
	v_lshlrev_b64 v[68:69], 11, v[68:69]
	s_add_i32 s74, s11, 0x14000
	s_add_i32 s11, s11, 0x16000
	v_lshl_add_u64 v[68:69], v[152:153], 0, v[68:69]
	s_mov_b32 s75, m0
	s_mov_b32 m0, s74
	s_nop 0
	global_load_lds_dwordx4 v[66:67], off
	s_mov_b32 m0, s11
	s_nop 0
	global_load_lds_dwordx4 v[68:69], off
	s_mov_b32 m0, s75

.LBB0_240:
	v_readlane_b32 s76, v252, 30
	v_readlane_b32 s77, v252, 31
	s_nop 4
	v_add3_u32 v66, s11, v155, v156
	s_andn2_b64 vcc, exec, s[76:77]
	s_andn2_b64 s[74:75], exec, s[76:77]
	v_add_u32_e32 v66, v66, v144
	ds_read_b64_tr_b16 v[174:175], v66 offset:8192
	ds_read_b64_tr_b16 v[176:177], v66 offset:8704
	ds_read_b64_tr_b16 v[178:179], v66 offset:9216
	ds_read_b64_tr_b16 v[180:181], v66 offset:9728
	ds_read_b64_tr_b16 v[182:183], v66 offset:10240
	ds_read_b64_tr_b16 v[184:185], v66 offset:10752
	ds_read_b64_tr_b16 v[186:187], v66 offset:11264
	ds_read_b64_tr_b16 v[188:189], v66 offset:11776
	ds_read_b64_tr_b16 v[190:191], v66 offset:12288
	ds_read_b64_tr_b16 v[192:193], v66 offset:12800
	ds_read_b64_tr_b16 v[194:195], v66 offset:13312
	ds_read_b64_tr_b16 v[196:197], v66 offset:13824
	s_cbranch_vccnz .LBB0_242
	s_waitcnt lgkmcnt(10)
	v_mfma_f32_32x32x16_bf16 v[16:31], v[174:177], v[114:117], v[16:31]
.LBB0_242:
	v_readlane_b32 vcc_lo, v252, 32
	v_readlane_b32 vcc_hi, v252, 33
	s_waitcnt lgkmcnt(8)
	v_mfma_f32_32x32x16_bf16 v[16:31], v[178:181], v[130:133], v[16:31]
	ds_read_b64_tr_b16 v[198:199], v66 offset:14336
	ds_read_b64_tr_b16 v[200:201], v66 offset:14848
	ds_read_b64_tr_b16 v[202:203], v66 offset:15360
	ds_read_b64_tr_b16 v[204:205], v66 offset:15872
	s_andn2_b64 s[76:77], exec, vcc
	s_andn2_b64 vcc, exec, vcc
	s_waitcnt lgkmcnt(10)
	v_mfma_f32_32x32x16_bf16 v[16:31], v[182:185], v[126:129], v[16:31]
	s_cbranch_vccnz .LBB0_244
	s_waitcnt lgkmcnt(8)
	v_mfma_f32_32x32x16_bf16 v[16:31], v[186:189], v[134:137], v[16:31]
